# v13 + one static s_setprio 1 for waves 0-3 during both attention phases (reset at phase exit)
# speedup vs baseline: 1.0084x; 1.0079x over previous
; __global__ void __launch_bounds__(NWAVES * 64, 2) mega_fwd(Args args) {
;     ...
;         if (layer == 0) {
;             for (int idx = vcu; idx < 1024 + 4096; idx += G) {
;                 size_t tok0; int head, kvh, qb, NT;
;                 if (idx < 1024) { const int xcd = (idx >> 5) & 7, j = idx & 31, i = idx >> 8; kvh = xcd & 3; const int w = (((xcd >> 2) * 4 + i) << 5) + j; head = kvh * 4 + (w >> 6); qb = w & 63; tok0 = MP; NT = LS / 64; }
;                 else { const int id2 = idx - 1024; const int xcd = (id2 >> 5) & 7, j = id2 & 31, i = id2 >> 8; const int gq = xcd * 16 + i; kvh = gq & 3; head = kvh * 4 + (j >> 3); qb = j & 7; tok0 = (size_t)(gq >> 2) * LP; NT = LP / 64; }
.LBB0_607:
	s_or_b64 exec, exec, s[4:5]
	s_cmpk_gt_i32 s72, 0x13ff
	s_waitcnt lgkmcnt(0)
	s_barrier
	s_cbranch_scc1 .LBB0_647
	v_readfirstlane_b32 s99, v182
	s_nop 3
	s_lshr_b32 s99, s99, 8
	s_cmp_eq_u32 s99, 0
	s_cbranch_scc0 .Lsprio_a0
	s_setprio 1
.Lsprio_a0:
	s_add_u32 s33, s30, 0x18000000
	s_addc_u32 s46, s31, 0
	s_add_u32 s47, s30, 0x22000000
	s_addc_u32 s48, s31, 0
	s_add_u32 s49, s30, 0x2c000000
	s_addc_u32 s50, s31, 0
	s_mov_b32 s5, 0
	v_mov_b32_e32 v159, 0
	s_mov_b32 s51, s72
	s_branch .LBB0_610

; __device__ __forceinline__ void xcd_barrier(const XcdBarrier& b) {
;     asm volatile("s_waitcnt vmcnt(0)" ::: "memory");
;     __syncthreads();
;     if (threadIdx.x == 0) {
;         unsigned* bar = b.bar;
;         __builtin_amdgcn_s_waitcnt(0);
;         unsigned nloc = b.st[0], nx = b.st[1];
;         if (nloc == 0u) { xcd_barrier_complete(bar, b.x, nloc, nx); b.st[0] = nloc; b.st[1] = nx; }
; __global__ void __launch_bounds__(NWAVES * 64, 2) mega_fwd(Args args) {
;     ...
;         xcd_barrier(xbar);
.LBB0_647:
	s_setprio 0
	s_waitcnt vmcnt(0)
	s_barrier
	s_mov_b64 s[4:5], exec
	v_readlane_b32 s6, v252, 1
	v_readlane_b32 s7, v252, 2
	s_and_b64 s[6:7], s[4:5], s[6:7]
	s_mov_b64 exec, s[6:7]
	s_cbranch_execz .LBB0_699
	s_add_i32 s6, 0, 0x25fc0
	v_mov_b32_e32 v0, s6
	s_waitcnt vmcnt(0) expcnt(0) lgkmcnt(0)
	ds_read_b32 v2, v0
	s_add_i32 s6, 0, 0x25fc4
	v_mov_b32_e32 v0, s6
	ds_read_b32 v0, v0
	s_waitcnt lgkmcnt(1)
	v_cmp_ne_u32_e32 vcc, 0, v2
	s_cbranch_vccnz .LBB0_663
	s_load_dword s6, s[0:1], 0xd8
	s_mov_b32 s42, 1
	v_mov_b32_e32 v16, 0
	s_waitcnt lgkmcnt(0)
	s_mul_i32 s33, s25, s6
	s_add_u32 s6, s26, 0x1000
	s_addc_u32 s7, s27, 0
	s_add_u32 s8, s26, 0x1100
	s_addc_u32 s9, s27, 0
	s_add_u32 s10, s26, 0x1200
	s_addc_u32 s11, s27, 0
	s_add_u32 s12, s26, 0x1300
	s_mul_i32 s33, s33, s24
	s_addc_u32 s13, s27, 0
	s_branch .LBB0_651

; __global__ void __launch_bounds__(NWAVES * 64, 2) mega_fwd(Args args) {
;     ...
;             const float s1 = wave_sum(ap->in[19][lane] * ap->in[20][lane]), s2 = wave_sum(ap->in[21][lane] * ap->in[22][lane]);
;             const float lam = expf(s1) - expf(s2) + LAMBDA_INIT1;
;             for (int idx = vcu; idx < 512 + 2048; idx += G) {
.LBB0_1066:
	s_or_b64 exec, exec, s[6:7]
	s_waitcnt lgkmcnt(0)
	s_barrier
	s_load_dwordx8 s[16:23], s[0:1], 0x98
	v_and_b32_e32 v4, 64, v157
	s_waitcnt lgkmcnt(0)
	global_load_dword v0, v156, s[16:17]
	global_load_dword v1, v156, s[18:19]
	global_load_dword v2, v156, s[20:21]
	global_load_dword v3, v156, s[22:23]
	v_xor_b32_e32 v5, 1, v157
	v_add_u32_e32 v4, 64, v4
	v_cmp_lt_i32_e32 vcc, v5, v4
	v_xor_b32_e32 v6, 2, v157
	v_xor_b32_e32 v7, 4, v157
	v_cndmask_b32_e32 v5, v157, v5, vcc
	v_lshlrev_b32_e32 v187, 2, v5
	v_cmp_lt_i32_e32 vcc, v6, v4
	v_xor_b32_e32 v8, 8, v157
	v_xor_b32_e32 v9, 16, v157
	v_cndmask_b32_e32 v6, v157, v6, vcc
	v_lshlrev_b32_e32 v188, 2, v6
	v_cmp_lt_i32_e32 vcc, v7, v4
	v_xor_b32_e32 v10, 32, v157
	s_cmpk_gt_i32 s72, 0x9ff
	s_mov_b32 s17, 0
	s_waitcnt vmcnt(2)
	v_mul_f32_e32 v5, v0, v1
	ds_bpermute_b32 v5, v187, v5
	s_waitcnt vmcnt(0)
	v_mul_f32_e32 v11, v2, v3
	ds_bpermute_b32 v11, v187, v11
	s_waitcnt lgkmcnt(1)
	v_fmac_f32_e32 v5, v0, v1
	ds_bpermute_b32 v0, v188, v5
	s_waitcnt lgkmcnt(1)
	v_fmac_f32_e32 v11, v2, v3
	ds_bpermute_b32 v1, v188, v11
	v_cndmask_b32_e32 v2, v157, v7, vcc
	v_lshlrev_b32_e32 v189, 2, v2
	s_waitcnt lgkmcnt(1)
	v_add_f32_e32 v0, v5, v0
	ds_bpermute_b32 v2, v189, v0
	s_waitcnt lgkmcnt(1)
	v_add_f32_e32 v1, v11, v1
	ds_bpermute_b32 v3, v189, v1
	v_cmp_lt_i32_e32 vcc, v8, v4
	s_waitcnt lgkmcnt(1)
	v_add_f32_e32 v0, v0, v2
	v_cndmask_b32_e32 v5, v157, v8, vcc
	v_lshlrev_b32_e32 v190, 2, v5
	s_waitcnt lgkmcnt(0)
	v_add_f32_e32 v1, v1, v3
	ds_bpermute_b32 v2, v190, v0
	ds_bpermute_b32 v3, v190, v1
	v_cmp_lt_i32_e32 vcc, v9, v4
	s_waitcnt lgkmcnt(1)
	v_add_f32_e32 v0, v0, v2
	v_cndmask_b32_e32 v5, v157, v9, vcc
	v_lshlrev_b32_e32 v183, 2, v5
	s_waitcnt lgkmcnt(0)
	v_add_f32_e32 v1, v1, v3
	ds_bpermute_b32 v2, v183, v0
	ds_bpermute_b32 v3, v183, v1
	v_cmp_lt_i32_e32 vcc, v10, v4
	s_waitcnt lgkmcnt(1)
	v_add_f32_e32 v2, v0, v2
	v_cndmask_b32_e32 v4, v157, v10, vcc
	v_lshlrev_b32_e32 v186, 2, v4
	s_waitcnt lgkmcnt(0)
	v_add_f32_e32 v0, v1, v3
	ds_bpermute_b32 v3, v186, v2
	ds_bpermute_b32 v1, v186, v0
	s_cbranch_scc1 .LBB0_1209
	s_waitcnt lgkmcnt(1)
	v_add_f32_e32 v2, v2, v3
	s_mov_b32 s18, 0x3fb8aa3b
	v_mul_f32_e32 v3, 0x3fb8aa3b, v2
	v_fma_f32 v4, v2, s18, -v3
	v_rndne_f32_e32 v5, v3
	v_fmac_f32_e32 v4, 0x32a5705f, v2
	v_sub_f32_e32 v3, v3, v5
	v_add_f32_e32 v3, v3, v4
	v_exp_f32_e32 v3, v3
	v_cvt_i32_f32_e32 v4, v5
	s_waitcnt lgkmcnt(0)
	v_add_f32_e32 v0, v0, v1
	s_mov_b32 s6, 0xc2ce8ed0
	v_cmp_ngt_f32_e32 vcc, s6, v2
	v_ldexp_f32 v1, v3, v4
	v_mul_f32_e32 v3, 0x3fb8aa3b, v0
	v_fma_f32 v4, v0, s18, -v3
	v_rndne_f32_e32 v5, v3
	v_fmac_f32_e32 v4, 0x32a5705f, v0
	v_sub_f32_e32 v3, v3, v5
	v_add_f32_e32 v3, v3, v4
	v_exp_f32_e32 v3, v3
	v_cvt_i32_f32_e32 v4, v5
	s_mov_b32 s7, 0x42b17218
	v_cndmask_b32_e32 v1, 0, v1, vcc
	v_mov_b32_e32 v5, 0x7f800000
	v_cmp_nlt_f32_e32 vcc, s7, v2
	v_ldexp_f32 v2, v3, v4
	s_load_dwordx2 s[20:21], s[0:1], 0x50
	v_cndmask_b32_e32 v1, v5, v1, vcc
	v_cmp_ngt_f32_e32 vcc, s6, v0
	v_readfirstlane_b32 s99, v182
	s_nop 3
	s_lshr_b32 s99, s99, 8
	s_cmp_eq_u32 s99, 0
	s_cbranch_scc0 .Lsprio_a1
	s_setprio 1
.Lsprio_a1:
	s_add_u32 s19, s30, 0x2c000000
	s_addc_u32 s62, s31, 0
	v_cndmask_b32_e32 v2, 0, v2, vcc
	v_cmp_nlt_f32_e32 vcc, s7, v0
	s_movk_i32 s63, 0x1ff
	s_movk_i32 s64, 0x300
	v_cndmask_b32_e32 v0, v5, v2, vcc
	v_sub_f32_e32 v0, v1, v0
	v_add_f32_e32 v191, 0x3eb60549, v0
	v_mov_b32_e32 v1, 0
	s_add_i32 s65, 0, 0x16000
	s_movk_i32 s66, 0x180
	s_movk_i32 s67, 0xff
	v_mov_b32_e32 v192, 0x358637bd
	s_branch .LBB0_1069

; __device__ __forceinline__ void xcd_barrier(const XcdBarrier& b) {
;     asm volatile("s_waitcnt vmcnt(0)" ::: "memory");
;     __syncthreads();
;     if (threadIdx.x == 0) {
;         unsigned* bar = b.bar;
;         __builtin_amdgcn_s_waitcnt(0);
;         unsigned nloc = b.st[0], nx = b.st[1];
;         if (nloc == 0u) { xcd_barrier_complete(bar, b.x, nloc, nx); b.st[0] = nloc; b.st[1] = nx; }
; __global__ void __launch_bounds__(NWAVES * 64, 2) mega_fwd(Args args) {
;     ...
;         xcd_barrier(xbar);
.LBB0_1209:
	s_setprio 0
	s_waitcnt vmcnt(0)
	s_waitcnt lgkmcnt(0)
	s_barrier
	s_mov_b64 s[6:7], exec
	v_readlane_b32 s8, v252, 1
	v_readlane_b32 s9, v252, 2
	s_and_b64 s[8:9], s[6:7], s[8:9]
	s_mov_b64 exec, s[8:9]
	s_cbranch_execz .LBB0_1261
	s_add_i32 s8, 0, 0x25fc0
	v_mov_b32_e32 v0, s8
	s_waitcnt vmcnt(0) expcnt(0) lgkmcnt(0)
	ds_read_b32 v2, v0
	s_add_i32 s8, 0, 0x25fc4
	v_mov_b32_e32 v0, s8
	ds_read_b32 v0, v0
	s_waitcnt lgkmcnt(1)
	v_cmp_ne_u32_e32 vcc, 0, v2
	s_cbranch_vccnz .LBB0_1225
	v_readlane_b32 s8, v252, 0
	s_mul_i32 s33, s25, s8
	s_add_u32 s8, s26, 0x1000
	s_addc_u32 s9, s27, 0
	s_add_u32 s10, s26, 0x1100
	s_addc_u32 s11, s27, 0
	s_add_u32 s16, s26, 0x1200
	s_addc_u32 s17, s27, 0
	s_add_u32 s18, s26, 0x1300
	s_mul_i32 s33, s33, s24
	s_addc_u32 s19, s27, 0
	s_mov_b32 s38, 1
	v_mov_b32_e32 v16, 0
	s_branch .LBB0_1213
